# P8 prologue: the 64 per-row partial sums for the RMSNorm scale are requested in one batch (one memory round trip instead of eight), same summation order
# speedup vs baseline: 1.0104x; 1.0092x over previous
; __global__ void __launch_bounds__(NWAVES * 64, 2) fwd(Args args) {
;     ...
;               for (int r = F.tid; r < 256; r += NWAVES * 64) { float sq = 0.f;
; #pragma unroll 8
;                   for (int p = 0; p < 64; ++p) sq += SSQ1[(size_t)p * T + pmx * 256 + r];
;                   rsl[(pmx - pm_lo) * 256 + r] = 1.0f / sqrtf(sq * (1.0f / D) + EPS); }
.LBB0_895:
	s_and_saveexec_b64 s[14:15], s[4:5]
	s_cbranch_execz .LBB0_894
	s_ashr_i32 s13, s12, 31
	s_lshl_b64 s[26:27], s[12:13], 2
	s_add_u32 s26, s26, s68
	s_addc_u32 s27, s27, s69
	s_add_u32 s26, s26, 0x43500000
	s_addc_u32 s27, s27, 0
	s_waitcnt vmcnt(0) lgkmcnt(0)
	global_load_dword v24, v162, s[26:27]
	s_add_u32 s26, s26, 0x8000
	s_addc_u32 s27, s27, 0
	global_load_dword v25, v162, s[26:27]
	s_add_u32 s26, s26, 0x8000
	s_addc_u32 s27, s27, 0
	global_load_dword v26, v162, s[26:27]
	s_add_u32 s26, s26, 0x8000
	s_addc_u32 s27, s27, 0
	global_load_dword v27, v162, s[26:27]
	s_add_u32 s26, s26, 0x8000
	s_addc_u32 s27, s27, 0
	global_load_dword v28, v162, s[26:27]
	s_add_u32 s26, s26, 0x8000
	s_addc_u32 s27, s27, 0
	global_load_dword v29, v162, s[26:27]
	s_add_u32 s26, s26, 0x8000
	s_addc_u32 s27, s27, 0
	global_load_dword v30, v162, s[26:27]
	s_add_u32 s26, s26, 0x8000
	s_addc_u32 s27, s27, 0
	global_load_dword v31, v162, s[26:27]
	s_add_u32 s26, s26, 0x8000
	s_addc_u32 s27, s27, 0
	global_load_dword v32, v162, s[26:27]
	s_add_u32 s26, s26, 0x8000
	s_addc_u32 s27, s27, 0
	global_load_dword v33, v162, s[26:27]
	s_add_u32 s26, s26, 0x8000
	s_addc_u32 s27, s27, 0
	global_load_dword v34, v162, s[26:27]
	s_add_u32 s26, s26, 0x8000
	s_addc_u32 s27, s27, 0
	global_load_dword v35, v162, s[26:27]
	s_add_u32 s26, s26, 0x8000
	s_addc_u32 s27, s27, 0
	global_load_dword v36, v162, s[26:27]
	s_add_u32 s26, s26, 0x8000
	s_addc_u32 s27, s27, 0
	global_load_dword v37, v162, s[26:27]
	s_add_u32 s26, s26, 0x8000
	s_addc_u32 s27, s27, 0
	global_load_dword v38, v162, s[26:27]
	s_add_u32 s26, s26, 0x8000
	s_addc_u32 s27, s27, 0
	global_load_dword v39, v162, s[26:27]
	s_add_u32 s26, s26, 0x8000
	s_addc_u32 s27, s27, 0
	global_load_dword v40, v162, s[26:27]
	s_add_u32 s26, s26, 0x8000
	s_addc_u32 s27, s27, 0
	global_load_dword v41, v162, s[26:27]
	s_add_u32 s26, s26, 0x8000
	s_addc_u32 s27, s27, 0
	global_load_dword v42, v162, s[26:27]
	s_add_u32 s26, s26, 0x8000
	s_addc_u32 s27, s27, 0
	global_load_dword v43, v162, s[26:27]
	s_add_u32 s26, s26, 0x8000
	s_addc_u32 s27, s27, 0
	global_load_dword v44, v162, s[26:27]
	s_add_u32 s26, s26, 0x8000
	s_addc_u32 s27, s27, 0
	global_load_dword v45, v162, s[26:27]
	s_add_u32 s26, s26, 0x8000
	s_addc_u32 s27, s27, 0
	global_load_dword v46, v162, s[26:27]
	s_add_u32 s26, s26, 0x8000
	s_addc_u32 s27, s27, 0
	global_load_dword v47, v162, s[26:27]
	s_add_u32 s26, s26, 0x8000
	s_addc_u32 s27, s27, 0
	global_load_dword v48, v162, s[26:27]
	s_add_u32 s26, s26, 0x8000
	s_addc_u32 s27, s27, 0
	global_load_dword v49, v162, s[26:27]
	s_add_u32 s26, s26, 0x8000
	s_addc_u32 s27, s27, 0
	global_load_dword v50, v162, s[26:27]
	s_add_u32 s26, s26, 0x8000
	s_addc_u32 s27, s27, 0
	global_load_dword v51, v162, s[26:27]
	s_add_u32 s26, s26, 0x8000
	s_addc_u32 s27, s27, 0
	global_load_dword v52, v162, s[26:27]
	s_add_u32 s26, s26, 0x8000
	s_addc_u32 s27, s27, 0
	global_load_dword v53, v162, s[26:27]
	s_add_u32 s26, s26, 0x8000
	s_addc_u32 s27, s27, 0
	global_load_dword v54, v162, s[26:27]
	s_add_u32 s26, s26, 0x8000
	s_addc_u32 s27, s27, 0
	global_load_dword v55, v162, s[26:27]
	s_add_u32 s26, s26, 0x8000
	s_addc_u32 s27, s27, 0
	global_load_dword v56, v162, s[26:27]
	s_add_u32 s26, s26, 0x8000
	s_addc_u32 s27, s27, 0
	global_load_dword v57, v162, s[26:27]
	s_add_u32 s26, s26, 0x8000
	s_addc_u32 s27, s27, 0
	global_load_dword v58, v162, s[26:27]
	s_add_u32 s26, s26, 0x8000
	s_addc_u32 s27, s27, 0
	global_load_dword v59, v162, s[26:27]
	s_add_u32 s26, s26, 0x8000
	s_addc_u32 s27, s27, 0
	global_load_dword v60, v162, s[26:27]
	s_add_u32 s26, s26, 0x8000
	s_addc_u32 s27, s27, 0
	global_load_dword v61, v162, s[26:27]
	s_add_u32 s26, s26, 0x8000
	s_addc_u32 s27, s27, 0
	global_load_dword v62, v162, s[26:27]
	s_add_u32 s26, s26, 0x8000
	s_addc_u32 s27, s27, 0
	global_load_dword v63, v162, s[26:27]
	s_add_u32 s26, s26, 0x8000
	s_addc_u32 s27, s27, 0
	global_load_dword v64, v162, s[26:27]
	s_add_u32 s26, s26, 0x8000
	s_addc_u32 s27, s27, 0
	global_load_dword v65, v162, s[26:27]
	s_add_u32 s26, s26, 0x8000
	s_addc_u32 s27, s27, 0
	global_load_dword v66, v162, s[26:27]
	s_add_u32 s26, s26, 0x8000
	s_addc_u32 s27, s27, 0
	global_load_dword v67, v162, s[26:27]
	s_add_u32 s26, s26, 0x8000
	s_addc_u32 s27, s27, 0
	global_load_dword v68, v162, s[26:27]
	s_add_u32 s26, s26, 0x8000
	s_addc_u32 s27, s27, 0
	global_load_dword v69, v162, s[26:27]
	s_add_u32 s26, s26, 0x8000
	s_addc_u32 s27, s27, 0
	global_load_dword v70, v162, s[26:27]
	s_add_u32 s26, s26, 0x8000
	s_addc_u32 s27, s27, 0
	global_load_dword v71, v162, s[26:27]
	s_add_u32 s26, s26, 0x8000
	s_addc_u32 s27, s27, 0
	global_load_dword v72, v162, s[26:27]
	s_add_u32 s26, s26, 0x8000
	s_addc_u32 s27, s27, 0
	global_load_dword v73, v162, s[26:27]
	s_add_u32 s26, s26, 0x8000
	s_addc_u32 s27, s27, 0
	global_load_dword v74, v162, s[26:27]
	s_add_u32 s26, s26, 0x8000
	s_addc_u32 s27, s27, 0
	global_load_dword v75, v162, s[26:27]
	s_add_u32 s26, s26, 0x8000
	s_addc_u32 s27, s27, 0
	global_load_dword v76, v162, s[26:27]
	s_add_u32 s26, s26, 0x8000
	s_addc_u32 s27, s27, 0
	global_load_dword v77, v162, s[26:27]
	s_add_u32 s26, s26, 0x8000
	s_addc_u32 s27, s27, 0
	global_load_dword v78, v162, s[26:27]
	s_add_u32 s26, s26, 0x8000
	s_addc_u32 s27, s27, 0
	global_load_dword v79, v162, s[26:27]
	s_add_u32 s26, s26, 0x8000
	s_addc_u32 s27, s27, 0
	global_load_dword v80, v162, s[26:27]
	s_add_u32 s26, s26, 0x8000
	s_addc_u32 s27, s27, 0
	global_load_dword v81, v162, s[26:27]
	s_add_u32 s26, s26, 0x8000
	s_addc_u32 s27, s27, 0
	global_load_dword v82, v162, s[26:27]
	s_add_u32 s26, s26, 0x8000
	s_addc_u32 s27, s27, 0
	global_load_dword v83, v162, s[26:27]
	s_add_u32 s26, s26, 0x8000
	s_addc_u32 s27, s27, 0
	global_load_dword v84, v162, s[26:27]
	s_add_u32 s26, s26, 0x8000
	s_addc_u32 s27, s27, 0
	global_load_dword v85, v162, s[26:27]
	s_add_u32 s26, s26, 0x8000
	s_addc_u32 s27, s27, 0
	global_load_dword v86, v162, s[26:27]
	s_add_u32 s26, s26, 0x8000
	s_addc_u32 s27, s27, 0
	global_load_dword v87, v162, s[26:27]
	v_mov_b32_e32 v9, 0
	s_waitcnt vmcnt(63)
; __global__ void __launch_bounds__(NWAVES * 64, 2) fwd(Args args) {
;     ...
;                   for (int p = 0; p < 64; ++p) sq += SSQ1[(size_t)p * T + pmx * 256 + r];
;                   rsl[(pmx - pm_lo) * 256 + r] = 1.0f / sqrtf(sq * (1.0f / D) + EPS); }
	v_add_f32_e32 v9, v9, v24
	s_waitcnt vmcnt(62)
	v_add_f32_e32 v9, v9, v25
	s_waitcnt vmcnt(61)
	v_add_f32_e32 v9, v9, v26
	s_waitcnt vmcnt(60)
	v_add_f32_e32 v9, v9, v27
	s_waitcnt vmcnt(59)
	v_add_f32_e32 v9, v9, v28
	s_waitcnt vmcnt(58)
	v_add_f32_e32 v9, v9, v29
	s_waitcnt vmcnt(57)
	v_add_f32_e32 v9, v9, v30
	s_waitcnt vmcnt(56)
	v_add_f32_e32 v9, v9, v31
	s_waitcnt vmcnt(55)
	v_add_f32_e32 v9, v9, v32
	s_waitcnt vmcnt(54)
	v_add_f32_e32 v9, v9, v33
	s_waitcnt vmcnt(53)
	v_add_f32_e32 v9, v9, v34
	s_waitcnt vmcnt(52)
	v_add_f32_e32 v9, v9, v35
	s_waitcnt vmcnt(51)
	v_add_f32_e32 v9, v9, v36
	s_waitcnt vmcnt(50)
	v_add_f32_e32 v9, v9, v37
	s_waitcnt vmcnt(49)
	v_add_f32_e32 v9, v9, v38
	s_waitcnt vmcnt(48)
	v_add_f32_e32 v9, v9, v39
	s_waitcnt vmcnt(47)
	v_add_f32_e32 v9, v9, v40
	s_waitcnt vmcnt(46)
	v_add_f32_e32 v9, v9, v41
	s_waitcnt vmcnt(45)
	v_add_f32_e32 v9, v9, v42
	s_waitcnt vmcnt(44)
	v_add_f32_e32 v9, v9, v43
	s_waitcnt vmcnt(43)
	v_add_f32_e32 v9, v9, v44
	s_waitcnt vmcnt(42)
	v_add_f32_e32 v9, v9, v45
	s_waitcnt vmcnt(41)
	v_add_f32_e32 v9, v9, v46
	s_waitcnt vmcnt(40)
	v_add_f32_e32 v9, v9, v47
	s_waitcnt vmcnt(39)
	v_add_f32_e32 v9, v9, v48
	s_waitcnt vmcnt(38)
	v_add_f32_e32 v9, v9, v49
	s_waitcnt vmcnt(37)
	v_add_f32_e32 v9, v9, v50
	s_waitcnt vmcnt(36)
	v_add_f32_e32 v9, v9, v51
	s_waitcnt vmcnt(35)
	v_add_f32_e32 v9, v9, v52
	s_waitcnt vmcnt(34)
	v_add_f32_e32 v9, v9, v53
	s_waitcnt vmcnt(33)
	v_add_f32_e32 v9, v9, v54
	s_waitcnt vmcnt(32)
	v_add_f32_e32 v9, v9, v55
	s_waitcnt vmcnt(31)
	v_add_f32_e32 v9, v9, v56
	s_waitcnt vmcnt(30)
	v_add_f32_e32 v9, v9, v57
	s_waitcnt vmcnt(29)
	v_add_f32_e32 v9, v9, v58
	s_waitcnt vmcnt(28)
	v_add_f32_e32 v9, v9, v59
	s_waitcnt vmcnt(27)
	v_add_f32_e32 v9, v9, v60
	s_waitcnt vmcnt(26)
	v_add_f32_e32 v9, v9, v61
	s_waitcnt vmcnt(25)
	v_add_f32_e32 v9, v9, v62
	s_waitcnt vmcnt(24)
	v_add_f32_e32 v9, v9, v63
	s_waitcnt vmcnt(23)
	v_add_f32_e32 v9, v9, v64
	s_waitcnt vmcnt(22)
	v_add_f32_e32 v9, v9, v65
	s_waitcnt vmcnt(21)
	v_add_f32_e32 v9, v9, v66
	s_waitcnt vmcnt(20)
	v_add_f32_e32 v9, v9, v67
	s_waitcnt vmcnt(19)
	v_add_f32_e32 v9, v9, v68
	s_waitcnt vmcnt(18)
	v_add_f32_e32 v9, v9, v69
	s_waitcnt vmcnt(17)
	v_add_f32_e32 v9, v9, v70
	s_waitcnt vmcnt(16)
	v_add_f32_e32 v9, v9, v71
	s_waitcnt vmcnt(15)
	v_add_f32_e32 v9, v9, v72
	s_waitcnt vmcnt(14)
	v_add_f32_e32 v9, v9, v73
	s_waitcnt vmcnt(13)
	v_add_f32_e32 v9, v9, v74
	s_waitcnt vmcnt(12)
	v_add_f32_e32 v9, v9, v75
	s_waitcnt vmcnt(11)
	v_add_f32_e32 v9, v9, v76
	s_waitcnt vmcnt(10)
	v_add_f32_e32 v9, v9, v77
	s_waitcnt vmcnt(9)
	v_add_f32_e32 v9, v9, v78
	s_waitcnt vmcnt(8)
	v_add_f32_e32 v9, v9, v79
	s_waitcnt vmcnt(7)
	v_add_f32_e32 v9, v9, v80
	s_waitcnt vmcnt(6)
	v_add_f32_e32 v9, v9, v81
	s_waitcnt vmcnt(5)
	v_add_f32_e32 v9, v9, v82
	s_waitcnt vmcnt(4)
	v_add_f32_e32 v9, v9, v83
	s_waitcnt vmcnt(3)
	v_add_f32_e32 v9, v9, v84
	s_waitcnt vmcnt(2)
	v_add_f32_e32 v9, v9, v85
	s_waitcnt vmcnt(1)
	v_add_f32_e32 v9, v9, v86
	s_waitcnt vmcnt(0)
	v_add_f32_e32 v9, v9, v87
	v_fmamk_f32 v4, v9, 0x39800000, v7
	v_mul_f32_e32 v5, 0x4f800000, v4
	v_cmp_gt_f32_e32 vcc, s18, v4
	s_nop 1
	v_cndmask_b32_e32 v4, v4, v5, vcc
	v_sqrt_f32_e32 v5, v4
	s_nop 0
	v_add_u32_e32 v9, -1, v5
	v_fma_f32 v11, -v9, v5, v4
	v_add_u32_e32 v10, 1, v5
	v_cmp_ge_f32_e64 s[6:7], 0, v11
	s_nop 1
	v_cndmask_b32_e64 v9, v5, v9, s[6:7]
	v_fma_f32 v5, -v10, v5, v4
	v_cmp_lt_f32_e64 s[6:7], 0, v5
	s_nop 1
	v_cndmask_b32_e64 v5, v9, v10, s[6:7]
	v_mul_f32_e32 v9, 0x37800000, v5
	v_cndmask_b32_e32 v5, v5, v9, vcc
	v_cmp_class_f32_e32 vcc, v4, v8
	s_nop 1
	v_cndmask_b32_e32 v4, v5, v4, vcc
	v_div_scale_f32 v5, s[6:7], v4, v4, 1.0
	v_rcp_f32_e32 v9, v5
	s_sub_i32 s6, s19, s16
	v_fma_f32 v10, -v5, v9, 1.0
	v_fmac_f32_e32 v9, v10, v9
	v_div_scale_f32 v10, vcc, 1.0, v4, 1.0
	v_mul_f32_e32 v11, v10, v9
	v_fma_f32 v12, -v5, v11, v10
	v_fmac_f32_e32 v11, v12, v9
	v_fma_f32 v5, -v5, v11, v10
	v_div_fmas_f32 v5, v5, v9, v11
	v_div_fixup_f32 v4, v5, v4, 1.0
	v_lshl_add_u32 v5, s6, 10, v6
	ds_write_b32 v5, v4
	s_branch .LBB0_894
